# P3 latent scan block: device-scope fence (L2 write-back + invalidate) before the workgroup-local y re-read replaced by completion wait + barrier, as the prompt scan block already does; loop heads re-p
# speedup vs baseline: 1.0163x; 1.0163x over previous
.LBB0_844:
	s_nop 3
	v_lshl_add_u64 v[0:1], s[22:23], 2, v[154:155]
	s_waitcnt vmcnt(0)
	s_barrier
	global_load_dwordx4 v[0:3], v[0:1], off
	s_add_u32 s6, s29, 0x2000
	s_addc_u32 s7, s28, 0
	s_lshl_b64 s[4:5], s[24:25], 17
	v_lshl_add_u64 v[4:5], v[158:159], 0, s[4:5]
	s_mov_b32 s20, 0
	s_mov_b64 s[24:25], -1

.LBB0_1057:
	s_add_i32 s41, s41, 1
	s_cmp_lt_i32 s41, s9
	s_mov_b64 s[24:25], s[12:13]
	s_cselect_b64 s[12:13], -1, 0
	s_cmp_eq_u32 s41, s9
	s_mov_b64 s[26:27], s[16:17]
	s_mov_b32 s44, s8
	s_cselect_b64 s[16:17], -1, 0
	s_min_i32 s8, s41, s9
	s_mul_i32 s8, s8, s92
	s_add_i32 s8, s8, s96
	s_min_i32 s8, s8, 0x9f
	s_ashr_i32 s22, s8, 31
	s_lshr_b32 s22, s22, 29
	s_add_i32 s22, s8, s22
	s_ashr_i32 s23, s22, 3
	s_and_b32 s22, s22, -8
	s_and_b64 s[16:17], s[16:17], s[4:5]
	s_sub_i32 s8, s8, s22
	s_cmp_lt_i32 s8, 0
	s_cselect_b32 s22, 21, 20
	s_mul_i32 s8, s8, s22
	s_add_i32 s8, s8, s23
	s_mul_hi_i32 s22, s8, 0x2aaaaaab
	s_lshr_b32 s23, s22, 31
	s_ashr_i32 s22, s22, 1
	s_add_i32 s22, s22, s23
	s_mul_i32 s28, s22, 3
	s_sub_i32 s23, 40, s28
	s_min_u32 s29, s23, 3
	s_mul_i32 s22, s22, 12
	s_sub_i32 s46, s8, s22
	v_cvt_f32_ubyte0_e32 v1, s29
	v_cvt_f32_i32_e32 v0, s46
	v_rcp_iflag_f32_e32 v2, v1
	s_ashr_i32 s8, s46, 30
	s_or_b32 s8, s8, 1
	s_mov_b32 s45, s34
	v_mul_f32_e32 v2, v0, v2
	v_trunc_f32_e32 v2, v2
	v_fma_f32 v0, -v2, v1, v0
	v_cvt_i32_f32_e32 v2, v2
	v_cmp_ge_f32_e64 s[22:23], |v0|, v1
	s_and_b64 s[22:23], s[22:23], exec
	s_cselect_b32 s8, s8, 0
	v_readfirstlane_b32 s22, v2
	s_add_i32 s8, s22, s8
	s_mul_i32 s22, s8, s29
	s_sub_i32 s22, s46, s22
	s_sext_i32_i8 s22, s22
	s_add_i32 s34, s28, s22
	s_or_b64 s[22:23], s[12:13], s[16:17]
	s_lshl_b32 s12, s34, 8
	s_ashr_i32 s13, s12, 31
	s_lshl_b64 s[12:13], s[12:13], 11
	s_add_u32 s12, s6, s12
	s_addc_u32 s13, s7, s13
	s_and_b64 s[16:17], s[22:23], exec
	s_cselect_b32 s46, s13, s25
	s_cselect_b32 s47, s12, s24
	s_bfe_i64 s[16:17], s[8:9], 0x80000
	s_lshl_b64 s[16:17], s[16:17], 19
	s_add_u32 s16, s30, s16
	s_addc_u32 s17, s31, s17
	s_and_b64 s[28:29], s[22:23], exec
	s_cselect_b32 s48, s17, s27
	s_cselect_b32 s49, s16, s26
	s_add_u32 s24, s24, 0x40080
	s_addc_u32 s25, s25, 0
	s_add_u32 s50, s26, 0x100
	v_mov_b32_e32 v0, 0
	s_addc_u32 s51, s27, 0
	s_mov_b32 s56, -2
	v_mov_b32_e32 v1, v0
	v_mov_b32_e32 v2, v0
	v_mov_b32_e32 v3, v0
	v_mov_b32_e32 v4, v0
	v_mov_b32_e32 v5, v0
	v_mov_b32_e32 v6, v0
	v_mov_b32_e32 v7, v0
	v_mov_b32_e32 v16, v0
	v_mov_b32_e32 v17, v0
	v_mov_b32_e32 v18, v0
	v_mov_b32_e32 v19, v0
	v_mov_b32_e32 v20, v0
	v_mov_b32_e32 v21, v0
	v_mov_b32_e32 v22, v0
	v_mov_b32_e32 v23, v0
	v_mov_b32_e32 v32, v0
	v_mov_b32_e32 v33, v0
	v_mov_b32_e32 v34, v0
	v_mov_b32_e32 v35, v0
	v_mov_b32_e32 v36, v0
	v_mov_b32_e32 v37, v0
	v_mov_b32_e32 v38, v0
	v_mov_b32_e32 v39, v0
	v_mov_b32_e32 v48, v0
	v_mov_b32_e32 v49, v0
	v_mov_b32_e32 v50, v0
	v_mov_b32_e32 v51, v0
	v_mov_b32_e32 v52, v0
	v_mov_b32_e32 v53, v0
	v_mov_b32_e32 v54, v0
	v_mov_b32_e32 v55, v0
	v_mov_b32_e32 v8, v0
	v_mov_b32_e32 v9, v0
	v_mov_b32_e32 v10, v0
	v_mov_b32_e32 v11, v0
	v_mov_b32_e32 v12, v0
	v_mov_b32_e32 v13, v0
	v_mov_b32_e32 v14, v0
	v_mov_b32_e32 v15, v0
	v_mov_b32_e32 v24, v0
	v_mov_b32_e32 v25, v0
	v_mov_b32_e32 v26, v0
	v_mov_b32_e32 v27, v0
	v_mov_b32_e32 v28, v0
	v_mov_b32_e32 v29, v0
	v_mov_b32_e32 v30, v0
	v_mov_b32_e32 v31, v0
	v_mov_b32_e32 v40, v0
	v_mov_b32_e32 v41, v0
	v_mov_b32_e32 v42, v0
	v_mov_b32_e32 v43, v0
	v_mov_b32_e32 v44, v0
	v_mov_b32_e32 v45, v0
	v_mov_b32_e32 v46, v0
	v_mov_b32_e32 v47, v0
	v_mov_b32_e32 v56, v0
	v_mov_b32_e32 v57, v0
	v_mov_b32_e32 v58, v0
	v_mov_b32_e32 v59, v0
	v_mov_b32_e32 v60, v0
	v_mov_b32_e32 v61, v0
	v_mov_b32_e32 v62, v0
	v_mov_b32_e32 v63, v0
	v_mov_b32_e32 v64, v0
	v_mov_b32_e32 v65, v0
	v_mov_b32_e32 v66, v0
	v_mov_b32_e32 v67, v0
	v_mov_b32_e32 v68, v0
	v_mov_b32_e32 v69, v0
	v_mov_b32_e32 v70, v0
	v_mov_b32_e32 v71, v0
	v_mov_b32_e32 v80, v0
	v_mov_b32_e32 v81, v0
	v_mov_b32_e32 v82, v0
	v_mov_b32_e32 v83, v0
	v_mov_b32_e32 v84, v0
	v_mov_b32_e32 v85, v0
	v_mov_b32_e32 v86, v0
	v_mov_b32_e32 v87, v0
	v_mov_b32_e32 v96, v0
	s_waitcnt lgkmcnt(0)
	v_mov_b32_e32 v97, v0
	v_mov_b32_e32 v98, v0
	v_mov_b32_e32 v99, v0
	v_mov_b32_e32 v100, v0
	v_mov_b32_e32 v101, v0
	v_mov_b32_e32 v102, v0
	v_mov_b32_e32 v103, v0
	v_mov_b32_e32 v112, v0
	v_mov_b32_e32 v113, v0
	v_mov_b32_e32 v114, v0
	v_mov_b32_e32 v115, v0
	v_mov_b32_e32 v116, v0
	v_mov_b32_e32 v117, v0
	v_mov_b32_e32 v118, v0
	v_mov_b32_e32 v119, v0
	v_mov_b32_e32 v72, v0
	v_mov_b32_e32 v73, v0
	v_mov_b32_e32 v74, v0
	v_mov_b32_e32 v75, v0
	v_mov_b32_e32 v76, v0
	v_mov_b32_e32 v77, v0
	v_mov_b32_e32 v78, v0
	v_mov_b32_e32 v79, v0
	v_mov_b32_e32 v88, v0
	v_mov_b32_e32 v89, v0
	v_mov_b32_e32 v90, v0
	v_mov_b32_e32 v91, v0
	v_mov_b32_e32 v92, v0
	v_mov_b32_e32 v93, v0
	v_mov_b32_e32 v94, v0
	v_mov_b32_e32 v95, v0
	v_mov_b32_e32 v104, v0
	v_mov_b32_e32 v105, v0
	v_mov_b32_e32 v106, v0
	v_mov_b32_e32 v107, v0
	v_mov_b32_e32 v108, v0
	v_mov_b32_e32 v109, v0
	v_mov_b32_e32 v110, v0
	v_mov_b32_e32 v111, v0
	v_mov_b32_e32 v120, v0
	v_mov_b32_e32 v121, v0
	v_mov_b32_e32 v122, v0
	v_mov_b32_e32 v123, v0
	v_mov_b32_e32 v124, v0
	v_mov_b32_e32 v125, v0
	v_mov_b32_e32 v126, v0
	v_mov_b32_e32 v127, v0
	s_nop 0
	s_nop 0
